# code placement: hand-written attention stream (and everything after it) shifted by 4 bytes
# baseline (speedup 1.0000x reference)
.LBB0_409:
	s_and_b64 vcc, exec, s[0:1]
	s_cbranch_vccz .LBB0_492
	v_readlane_b32 s0, v255, 12
	s_cmpk_gt_i32 s0, 0x7ff
	s_cbranch_scc1 .LBB0_492
	s_nop 0
	s_mov_b32 s24, m0
	v_readfirstlane_b32 s4, v198
	v_readlane_b32 s38, v255, 12
	s_lshr_b32 s27, s4, 6
	s_lshl_b32 s16, s27, 10
	s_lshr_b32 s2, s27, 2
	s_cmp_eq_u32 s2, 1
	s_cbranch_scc0 .Lat2_noprio
	s_setprio 1
